# v63 + nt hint on the phase-A tail weight-conversion loads/stores (protects the co-running GEMM units' L2 lines)
# speedup vs baseline: 1.0059x; 1.0059x over previous
; #define LAS __attribute__((address_space(3)))
; #define LDS_WAIT() asm volatile("s_waitcnt lgkmcnt(0)" ::: "memory")
; __device__ __forceinline__ unsigned pk2(float lo, float hi) { return pg8::cvt_pk_bf16(lo, hi); }
; __device__ __forceinline__ void transpose_item(const float* W, const float* g, int K, int N, bf16* WT, LAS float* scr, int item, int lane) {
;     ...
;     for (int i = 0; i < 16; ++i) { LAS float* d = scr + (4 * i + kr) * 65 + 4 * n4; d[0] = w[i].x; d[1] = w[i].y; d[2] = w[i].z; d[3] = w[i].w; }
;     LDS_WAIT(); asm volatile("" ::: "memory");
;     const int c = lane & 7;
; #pragma unroll
;     for (int j = 0; j < 8; ++j) { const int n = (lane >> 3) + 8 * j; const LAS float* s = scr + (8 * c) * 65 + n;
;         v4u o; o.x = pk2(s[0 * 65], s[1 * 65]); o.y = pk2(s[2 * 65], s[3 * 65]); o.z = pk2(s[4 * 65], s[5 * 65]); o.w = pk2(s[6 * 65], s[7 * 65]);
;         *(v4u*)(WT + (size_t)(n0 + n) * K + k0 + 8 * c) = o; }
;     LDS_WAIT(); asm volatile("" ::: "memory");
.LBB0_169:
	s_waitcnt vmcnt(0)
	v_add_u32_e32 v106, v77, v78
	ds_write2_b32 v106, v58, v59 offset1:1
	ds_write2_b32 v106, v60, v61 offset0:2 offset1:3
	ds_write2_b32 v105, v50, v51 offset1:1
	ds_write2_b32 v105, v52, v53 offset0:2 offset1:3
	v_add_u32_e32 v50, 0x410, v105
	ds_write2_b32 v50, v62, v63 offset1:1
	v_add_u32_e32 v50, 0x418, v105
	ds_write2_b32 v50, v64, v65 offset1:1
	v_add_u32_e32 v50, 0x820, v105
	ds_write2_b32 v50, v42, v43 offset1:1
	v_add_u32_e32 v42, 0x828, v105
	ds_write2_b32 v42, v44, v45 offset1:1
	v_add_u32_e32 v42, 0xc30, v105
	ds_write2_b32 v42, v54, v55 offset1:1
	v_add_u32_e32 v42, 0xc38, v105
	ds_write2_b32 v42, v56, v57 offset1:1
	v_add_u32_e32 v42, 0x1040, v105
	ds_write2_b32 v42, v34, v35 offset1:1
	v_add_u32_e32 v34, 0x1048, v105
	ds_write2_b32 v34, v36, v37 offset1:1
	v_add_u32_e32 v34, 0x1450, v105
	ds_write2_b32 v34, v46, v47 offset1:1
	v_add_u32_e32 v34, 0x1458, v105
	ds_write2_b32 v34, v48, v49 offset1:1
	v_add_u32_e32 v34, 0x1860, v105
	ds_write2_b32 v34, v26, v27 offset1:1
	v_add_u32_e32 v26, 0x1868, v105
	ds_write2_b32 v26, v28, v29 offset1:1
	v_add_u32_e32 v26, 0x1c70, v105
	ds_write2_b32 v26, v38, v39 offset1:1
	v_add_u32_e32 v26, 0x1c78, v105
	ds_write2_b32 v26, v40, v41 offset1:1
	v_add_u32_e32 v26, 0x2080, v105
	ds_write2_b32 v26, v18, v19 offset1:1
	v_add_u32_e32 v18, 0x2088, v105
	ds_write2_b32 v18, v20, v21 offset1:1
	v_add_u32_e32 v18, 0x2490, v105
	ds_write2_b32 v18, v30, v31 offset1:1
	v_add_u32_e32 v18, 0x2498, v105
	ds_write2_b32 v18, v32, v33 offset1:1
	v_add_u32_e32 v18, 0x28a0, v105
	ds_write2_b32 v18, v10, v11 offset1:1
	v_add_u32_e32 v10, 0x28a8, v105
	ds_write2_b32 v10, v12, v13 offset1:1
	v_add_u32_e32 v10, 0x2cb0, v105
	ds_write2_b32 v10, v22, v23 offset1:1
	v_add_u32_e32 v10, 0x2cb8, v105
	ds_write2_b32 v10, v24, v25 offset1:1
	v_add_u32_e32 v10, 0x30c0, v105
	ds_write2_b32 v10, v6, v7 offset1:1
	v_add_u32_e32 v6, 0x30c8, v105
	ds_write2_b32 v6, v8, v9 offset1:1
	v_add_u32_e32 v6, 0x34d0, v105
	ds_write2_b32 v6, v14, v15 offset1:1
	v_add_u32_e32 v6, 0x34d8, v105
	ds_write2_b32 v6, v16, v17 offset1:1
	v_add_u32_e32 v6, 0x38e0, v105
	ds_write2_b32 v6, v2, v3 offset1:1
	v_add_u32_e32 v2, 0x38e8, v105
	ds_write2_b32 v2, v4, v5 offset1:1
	s_waitcnt lgkmcnt(0)
	v_add_u32_e32 v28, 0x400, v80
	ds_read2_b32 v[6:7], v80 offset0:65 offset1:73
	ds_read2_b32 v[8:9], v80 offset1:8
	ds_read2_b32 v[10:11], v80 offset0:130 offset1:138
	ds_read2_b32 v[12:13], v80 offset0:195 offset1:203
	ds_read2_b32 v[14:15], v28 offset0:4 offset1:12
	ds_read2_b32 v[16:17], v28 offset0:69 offset1:77
	ds_read2_b32 v[18:19], v28 offset0:134 offset1:142
	ds_read2_b32 v[20:21], v28 offset0:199 offset1:207
	v_add_u32_e32 v24, s16, v79
	s_ashr_i32 s1, s0, 31
	v_ashrrev_i32_e32 v25, 31, v24
	v_lshl_add_u64 v[22:23], s[0:1], 1, v[74:75]
	v_lshlrev_b64 v[26:27], 12, v[24:25]
	s_waitcnt lgkmcnt(6)
	v_cvt_pk_bf16_f32 v2, v8, v6
	s_waitcnt lgkmcnt(4)
	v_cvt_pk_bf16_f32 v3, v10, v12
	s_waitcnt lgkmcnt(2)
	v_cvt_pk_bf16_f32 v4, v14, v16
	s_waitcnt lgkmcnt(0)
	v_cvt_pk_bf16_f32 v5, v18, v20
	v_lshl_add_u64 v[26:27], v[22:23], 0, v[26:27]
	v_add_u32_e32 v6, 8, v24
	global_store_dwordx4 v[26:27], v[2:5], off nt
	s_nop 1
	v_cvt_pk_bf16_f32 v2, v9, v7
	v_ashrrev_i32_e32 v7, 31, v6
	v_cvt_pk_bf16_f32 v3, v11, v13
	v_cvt_pk_bf16_f32 v4, v15, v17
	v_cvt_pk_bf16_f32 v5, v19, v21
	v_lshlrev_b64 v[6:7], 12, v[6:7]
	ds_read2_b32 v[8:9], v80 offset0:81 offset1:89
	ds_read2_b32 v[10:11], v80 offset0:16 offset1:24
	ds_read2_b32 v[12:13], v80 offset0:146 offset1:154
	ds_read2_b32 v[14:15], v80 offset0:211 offset1:219
	ds_read2_b32 v[16:17], v28 offset0:20 offset1:28
	ds_read2_b32 v[18:19], v28 offset0:85 offset1:93
	ds_read2_b32 v[20:21], v28 offset0:150 offset1:158
	ds_read2_b32 v[26:27], v28 offset0:215 offset1:223
	v_lshl_add_u64 v[6:7], v[22:23], 0, v[6:7]
	global_store_dwordx4 v[6:7], v[2:5], off nt
	v_add_u32_e32 v6, 16, v24
	v_ashrrev_i32_e32 v7, 31, v6
	v_lshlrev_b64 v[6:7], 12, v[6:7]
	s_waitcnt lgkmcnt(6)
	v_cvt_pk_bf16_f32 v2, v10, v8
	s_waitcnt lgkmcnt(4)
	v_cvt_pk_bf16_f32 v3, v12, v14
	s_waitcnt lgkmcnt(2)
	v_cvt_pk_bf16_f32 v4, v16, v18
	s_waitcnt lgkmcnt(0)
	v_cvt_pk_bf16_f32 v5, v20, v26
	v_lshl_add_u64 v[6:7], v[22:23], 0, v[6:7]
	global_store_dwordx4 v[6:7], v[2:5], off nt
	v_add_u32_e32 v6, 24, v24
	v_ashrrev_i32_e32 v7, 31, v6
	v_cvt_pk_bf16_f32 v2, v11, v9
	v_cvt_pk_bf16_f32 v3, v13, v15
	v_cvt_pk_bf16_f32 v4, v17, v19
	v_cvt_pk_bf16_f32 v5, v21, v27
	v_lshlrev_b64 v[6:7], 12, v[6:7]
	ds_read2_b32 v[8:9], v80 offset0:32 offset1:40
	ds_read2_b32 v[10:11], v80 offset0:97 offset1:105
	ds_read2_b32 v[12:13], v80 offset0:162 offset1:170
	ds_read2_b32 v[14:15], v80 offset0:227 offset1:235
	ds_read2_b32 v[16:17], v28 offset0:36 offset1:44
	ds_read2_b32 v[18:19], v28 offset0:101 offset1:109
	ds_read2_b32 v[20:21], v28 offset0:166 offset1:174
	ds_read2_b32 v[26:27], v28 offset0:231 offset1:239
	v_lshl_add_u64 v[6:7], v[22:23], 0, v[6:7]
	global_store_dwordx4 v[6:7], v[2:5], off nt
	v_add_u32_e32 v6, 32, v24
	v_ashrrev_i32_e32 v7, 31, v6
	v_lshlrev_b64 v[6:7], 12, v[6:7]
	s_waitcnt lgkmcnt(6)
	v_cvt_pk_bf16_f32 v2, v8, v10
	s_waitcnt lgkmcnt(4)
	v_cvt_pk_bf16_f32 v3, v12, v14
	s_waitcnt lgkmcnt(2)
	v_cvt_pk_bf16_f32 v4, v16, v18
	s_waitcnt lgkmcnt(0)
	v_cvt_pk_bf16_f32 v5, v20, v26
	v_lshl_add_u64 v[6:7], v[22:23], 0, v[6:7]
	global_store_dwordx4 v[6:7], v[2:5], off nt
	v_add_u32_e32 v6, 40, v24
	v_ashrrev_i32_e32 v7, 31, v6
	v_cvt_pk_bf16_f32 v2, v9, v11
	v_cvt_pk_bf16_f32 v3, v13, v15
	v_cvt_pk_bf16_f32 v4, v17, v19
	v_cvt_pk_bf16_f32 v5, v21, v27
	v_lshlrev_b64 v[6:7], 12, v[6:7]
	ds_read2_b32 v[8:9], v80 offset0:48 offset1:56
	ds_read2_b32 v[10:11], v80 offset0:113 offset1:121
	ds_read2_b32 v[12:13], v80 offset0:178 offset1:186
	ds_read2_b32 v[14:15], v80 offset0:243 offset1:251
	ds_read2_b32 v[16:17], v28 offset0:52 offset1:60
	ds_read2_b32 v[18:19], v28 offset0:117 offset1:125
	ds_read2_b32 v[20:21], v28 offset0:182 offset1:190
	ds_read2_b32 v[26:27], v28 offset0:247 offset1:255
	v_lshl_add_u64 v[6:7], v[22:23], 0, v[6:7]
	global_store_dwordx4 v[6:7], v[2:5], off nt
	v_add_u32_e32 v6, 48, v24
	v_ashrrev_i32_e32 v7, 31, v6
	v_lshlrev_b64 v[6:7], 12, v[6:7]
	s_waitcnt lgkmcnt(6)
	v_cvt_pk_bf16_f32 v2, v8, v10
	s_waitcnt lgkmcnt(4)
	v_cvt_pk_bf16_f32 v3, v12, v14
	s_waitcnt lgkmcnt(2)
	v_cvt_pk_bf16_f32 v4, v16, v18
	s_waitcnt lgkmcnt(0)
	v_cvt_pk_bf16_f32 v5, v20, v26
	v_lshl_add_u64 v[6:7], v[22:23], 0, v[6:7]
	global_store_dwordx4 v[6:7], v[2:5], off nt
	v_add_u32_e32 v6, 56, v24
	v_ashrrev_i32_e32 v7, 31, v6
	v_lshlrev_b64 v[6:7], 12, v[6:7]
	v_cvt_pk_bf16_f32 v2, v9, v11
	v_cvt_pk_bf16_f32 v3, v13, v15
	v_cvt_pk_bf16_f32 v4, v17, v19
	v_cvt_pk_bf16_f32 v5, v21, v27
	v_lshl_add_u64 v[6:7], v[22:23], 0, v[6:7]
	global_store_dwordx4 v[6:7], v[2:5], off nt
	s_waitcnt lgkmcnt(0)

; #define LAS __attribute__((address_space(3)))
; __device__ __forceinline__ void transpose_item(const float* W, const float* g, int K, int N, bf16* WT, LAS float* scr, int item, int lane) {
;     const int nblk = N / 64, kb = item / nblk, nb = item % nblk, k0 = 64 * kb, n0 = 64 * nb;
;     const int n4 = lane & 15, kr = lane >> 4;
;     f32x4 w[16];
;     const float gl = g ? g[k0 + lane] : 1.f;
; #pragma unroll
;     for (int i = 0; i < 16; ++i) w[i] = *(const f32x4*)(W + (size_t)(k0 + 4 * i + kr) * N + n0 + 4 * n4);
;     if (g) {
; #pragma unroll
;         for (int i = 0; i < 16; ++i) w[i] = w[i] * __shfl(gl, 4 * i + kr); }
; #pragma unroll
;     for (int i = 0; i < 16; ++i) { LAS float* d = scr + (4 * i + kr) * 65 + 4 * n4; d[0] = w[i].x; d[1] = w[i].y; d[2] = w[i].z; d[3] = w[i].w; }
.LBB0_171:
	s_cmpk_gt_i32 s28, 0x14ff
	s_mov_b64 s[0:1], -1
	s_cbranch_scc0 .LBB0_186
	s_cmpk_gt_u32 s28, 0x18ff
	s_cbranch_scc0 .LBB0_183
	s_cmpk_gt_u32 s28, 0x28ff
	s_cbranch_scc0 .LBB0_175
	s_load_dwordx2 s[0:1], s[18:19], 0x20
	v_lshlrev_b32_e32 v158, 2, v66
	v_add_u32_e32 v106, v77, v78
	v_add_u32_e32 v107, 0x410, v106
	s_waitcnt lgkmcnt(0)
	s_add_u32 s16, s0, s12
	s_addc_u32 s1, s1, s13
	s_and_b32 s0, s21, 0x7c0
	s_and_b32 s22, s29, 0x1ffc0
	s_lshl_b32 s17, s0, 2
	s_add_u32 s16, s16, s17
	v_or_b32_e32 v4, s22, v76
	s_addc_u32 s17, s1, 0
	v_lshl_add_u64 v[2:3], s[16:17], 0, v[158:159]
	v_lshlrev_b32_e32 v158, 13, v4
	v_lshl_add_u64 v[62:63], v[2:3], 0, v[158:159]
	s_mov_b32 s1, 0x8000
	v_add_co_u32_e32 v6, vcc, s1, v62
	s_mov_b32 s1, 0x10000
	s_nop 0
	v_addc_co_u32_e32 v7, vcc, 0, v63, vcc
	v_add_co_u32_e32 v10, vcc, s1, v62
	global_load_dwordx4 v[2:5], v[62:63], off nt
	s_nop 0
	global_load_dwordx4 v[6:9], v[6:7], off nt
	v_addc_co_u32_e32 v11, vcc, 0, v63, vcc
	s_mov_b32 s1, 0x18000
	v_add_co_u32_e32 v14, vcc, s1, v62
	s_mov_b32 s1, 0x20000
	s_nop 0
	v_addc_co_u32_e32 v15, vcc, 0, v63, vcc
	global_load_dwordx4 v[10:13], v[10:11], off nt
	s_nop 0
	global_load_dwordx4 v[14:17], v[14:15], off nt
	v_add_co_u32_e32 v18, vcc, s1, v62
	s_mov_b32 s1, 0x28000
	s_nop 0
	v_addc_co_u32_e32 v19, vcc, 0, v63, vcc
	v_add_co_u32_e32 v22, vcc, s1, v62
	s_mov_b32 s1, 0x30000
	s_nop 0
	v_addc_co_u32_e32 v23, vcc, 0, v63, vcc
	global_load_dwordx4 v[18:21], v[18:19], off nt
	s_nop 0
	global_load_dwordx4 v[22:25], v[22:23], off nt
	v_add_co_u32_e32 v26, vcc, s1, v62
	s_mov_b32 s1, 0x38000
	s_nop 0
	v_addc_co_u32_e32 v27, vcc, 0, v63, vcc
	v_add_co_u32_e32 v30, vcc, s1, v62
	s_mov_b32 s1, 0x40000
	s_nop 0
	v_addc_co_u32_e32 v31, vcc, 0, v63, vcc
	global_load_dwordx4 v[26:29], v[26:27], off nt
	s_nop 0
	global_load_dwordx4 v[30:33], v[30:31], off nt
	v_add_co_u32_e32 v34, vcc, s1, v62
	s_mov_b32 s1, 0x48000
	s_nop 0
	v_addc_co_u32_e32 v35, vcc, 0, v63, vcc
	v_add_co_u32_e32 v38, vcc, s1, v62
	s_mov_b32 s1, 0x50000
	s_nop 0
	v_addc_co_u32_e32 v39, vcc, 0, v63, vcc
	global_load_dwordx4 v[34:37], v[34:35], off nt
	s_nop 0
	global_load_dwordx4 v[38:41], v[38:39], off nt
	v_add_co_u32_e32 v42, vcc, s1, v62
	s_mov_b32 s1, 0x58000
	s_nop 0
	v_addc_co_u32_e32 v43, vcc, 0, v63, vcc
	v_add_co_u32_e32 v46, vcc, s1, v62
	s_mov_b32 s1, 0x60000
	s_nop 0
	v_addc_co_u32_e32 v47, vcc, 0, v63, vcc
	global_load_dwordx4 v[42:45], v[42:43], off nt
	s_nop 0
	global_load_dwordx4 v[46:49], v[46:47], off nt
	v_add_co_u32_e32 v50, vcc, s1, v62
	s_mov_b32 s1, 0x68000
	s_nop 0
	v_addc_co_u32_e32 v51, vcc, 0, v63, vcc
	global_load_dwordx4 v[50:53], v[50:51], off nt
	v_add_co_u32_e32 v54, vcc, s1, v62
	s_mov_b32 s1, 0x70000
	s_nop 0
	v_addc_co_u32_e32 v55, vcc, 0, v63, vcc
	global_load_dwordx4 v[54:57], v[54:55], off nt
	v_add_co_u32_e32 v58, vcc, s1, v62
	s_mov_b32 s1, 0x78000
	s_nop 0
	v_addc_co_u32_e32 v59, vcc, 0, v63, vcc
	global_load_dwordx4 v[58:61], v[58:59], off nt
	v_add_co_u32_e32 v62, vcc, s1, v62
	s_lshl_b32 s34, s22, 1
	s_nop 0
	v_addc_co_u32_e32 v63, vcc, 0, v63, vcc
	global_load_dwordx4 v[62:65], v[62:63], off nt
	s_waitcnt vmcnt(0)
	ds_write2_b32 v106, v2, v3 offset1:1
	ds_write2_b32 v106, v4, v5 offset0:2 offset1:3
	ds_write2_b32 v107, v6, v7 offset1:1
	v_add_u32_e32 v2, 0x418, v106
	ds_write2_b32 v2, v8, v9 offset1:1
	v_add_u32_e32 v2, 0x820, v106
	ds_write2_b32 v2, v10, v11 offset1:1
	v_add_u32_e32 v2, 0x828, v106
	ds_write2_b32 v2, v12, v13 offset1:1
	v_add_u32_e32 v2, 0xc30, v106
	ds_write2_b32 v2, v14, v15 offset1:1
	v_add_u32_e32 v2, 0xc38, v106
	ds_write2_b32 v2, v16, v17 offset1:1
	v_add_u32_e32 v2, 0x1040, v106
	ds_write2_b32 v2, v18, v19 offset1:1
	v_add_u32_e32 v2, 0x1048, v106
	ds_write2_b32 v2, v20, v21 offset1:1
	v_add_u32_e32 v2, 0x1450, v106
	ds_write2_b32 v2, v22, v23 offset1:1
	v_add_u32_e32 v2, 0x1458, v106
	ds_write2_b32 v2, v24, v25 offset1:1
	v_add_u32_e32 v2, 0x1860, v106
	v_lshl_add_u64 v[22:23], v[68:69], 0, s[34:35]
	ds_write2_b32 v2, v26, v27 offset1:1
	v_add_u32_e32 v2, 0x1868, v106
	ds_write2_b32 v2, v28, v29 offset1:1
	v_add_u32_e32 v2, 0x1c70, v106
	ds_write2_b32 v2, v30, v31 offset1:1
	v_add_u32_e32 v2, 0x1c78, v106
	ds_write2_b32 v2, v32, v33 offset1:1
	v_add_u32_e32 v2, 0x2080, v106
	v_add_u32_e32 v26, 0x400, v80
	ds_write2_b32 v2, v34, v35 offset1:1
	v_add_u32_e32 v2, 0x2088, v106
	ds_write2_b32 v2, v36, v37 offset1:1
	v_add_u32_e32 v2, 0x2490, v106
	ds_write2_b32 v2, v38, v39 offset1:1
	v_add_u32_e32 v2, 0x2498, v106
	ds_write2_b32 v2, v40, v41 offset1:1
	v_add_u32_e32 v2, 0x28a0, v106
	ds_write2_b32 v2, v42, v43 offset1:1
	v_add_u32_e32 v2, 0x28a8, v106
	ds_write2_b32 v2, v44, v45 offset1:1
	v_add_u32_e32 v2, 0x2cb0, v106
	ds_write2_b32 v2, v46, v47 offset1:1
	v_add_u32_e32 v2, 0x2cb8, v106
	ds_write2_b32 v2, v48, v49 offset1:1
	v_add_u32_e32 v2, 0x30c0, v106
	ds_write2_b32 v2, v50, v51 offset1:1
	v_add_u32_e32 v2, 0x30c8, v106
	ds_write2_b32 v2, v52, v53 offset1:1
	v_add_u32_e32 v2, 0x34d0, v106
	ds_write2_b32 v2, v54, v55 offset1:1
	v_add_u32_e32 v2, 0x34d8, v106
	ds_write2_b32 v2, v56, v57 offset1:1
	v_add_u32_e32 v2, 0x38e0, v106
	ds_write2_b32 v2, v58, v59 offset1:1
	v_add_u32_e32 v2, 0x38e8, v106
	ds_write2_b32 v2, v60, v61 offset1:1
	v_add_u32_e32 v2, 0x3cf0, v106
	ds_write2_b32 v2, v62, v63 offset1:1
	v_add_u32_e32 v2, 0x3cf8, v106
	ds_write2_b32 v2, v64, v65 offset1:1
	s_waitcnt lgkmcnt(0)
; #define LAS __attribute__((address_space(3)))
; #define LDS_WAIT() asm volatile("s_waitcnt lgkmcnt(0)" ::: "memory")
; __device__ __forceinline__ unsigned pk2(float lo, float hi) { return pg8::cvt_pk_bf16(lo, hi); }
; __device__ __forceinline__ void transpose_item(const float* W, const float* g, int K, int N, bf16* WT, LAS float* scr, int item, int lane) {
;     ...
;     const float gl = g ? g[k0 + lane] : 1.f;
;     ...
;     LDS_WAIT(); asm volatile("" ::: "memory");
;     const int c = lane & 7;
; #pragma unroll
;     for (int j = 0; j < 8; ++j) { const int n = (lane >> 3) + 8 * j; const LAS float* s = scr + (8 * c) * 65 + n;
;         v4u o; o.x = pk2(s[0 * 65], s[1 * 65]); o.y = pk2(s[2 * 65], s[3 * 65]); o.z = pk2(s[4 * 65], s[5 * 65]); o.w = pk2(s[6 * 65], s[7 * 65]);
;         *(v4u*)(WT + (size_t)(n0 + n) * K + k0 + 8 * c) = o; }
;     LDS_WAIT(); asm volatile("" ::: "memory");
	ds_read2_b32 v[6:7], v80 offset0:65 offset1:73
	ds_read2_b32 v[8:9], v80 offset1:8
	ds_read2_b32 v[10:11], v80 offset0:130 offset1:138
	ds_read2_b32 v[12:13], v80 offset0:195 offset1:203
	ds_read2_b32 v[14:15], v26 offset0:4 offset1:12
	ds_read2_b32 v[16:17], v26 offset0:69 offset1:77
	ds_read2_b32 v[18:19], v26 offset0:134 offset1:142
	ds_read2_b32 v[20:21], v26 offset0:199 offset1:207
	s_waitcnt lgkmcnt(6)
	v_cvt_pk_bf16_f32 v2, v8, v6
	v_or_b32_e32 v6, s0, v79
	v_lshlrev_b32_e32 v158, 14, v6
	s_waitcnt lgkmcnt(4)
	v_cvt_pk_bf16_f32 v3, v10, v12
	s_waitcnt lgkmcnt(2)
	v_cvt_pk_bf16_f32 v4, v14, v16
	s_waitcnt lgkmcnt(0)
	v_cvt_pk_bf16_f32 v5, v18, v20
	v_lshl_add_u64 v[24:25], v[22:23], 0, v[158:159]
	global_store_dwordx4 v[24:25], v[2:5], off nt
	v_or_b32_e32 v6, s0, v81
	v_lshlrev_b32_e32 v158, 14, v6
	v_cvt_pk_bf16_f32 v2, v9, v7
	v_cvt_pk_bf16_f32 v3, v11, v13
	v_cvt_pk_bf16_f32 v4, v15, v17
	v_cvt_pk_bf16_f32 v5, v19, v21
	ds_read2_b32 v[8:9], v80 offset0:81 offset1:89
	ds_read2_b32 v[10:11], v80 offset0:16 offset1:24
	ds_read2_b32 v[12:13], v80 offset0:146 offset1:154
	ds_read2_b32 v[14:15], v80 offset0:211 offset1:219
	ds_read2_b32 v[16:17], v26 offset0:20 offset1:28
	ds_read2_b32 v[18:19], v26 offset0:85 offset1:93
	ds_read2_b32 v[20:21], v26 offset0:150 offset1:158
	ds_read2_b32 v[24:25], v26 offset0:215 offset1:223
	v_lshl_add_u64 v[6:7], v[22:23], 0, v[158:159]
	global_store_dwordx4 v[6:7], v[2:5], off nt
	v_or_b32_e32 v6, s0, v82
	v_lshlrev_b32_e32 v158, 14, v6
	s_waitcnt lgkmcnt(6)
	v_cvt_pk_bf16_f32 v2, v10, v8
	s_waitcnt lgkmcnt(4)
	v_cvt_pk_bf16_f32 v3, v12, v14
	s_waitcnt lgkmcnt(2)
	v_cvt_pk_bf16_f32 v4, v16, v18
	s_waitcnt lgkmcnt(0)
	v_cvt_pk_bf16_f32 v5, v20, v24
	v_lshl_add_u64 v[6:7], v[22:23], 0, v[158:159]
	global_store_dwordx4 v[6:7], v[2:5], off nt
	v_or_b32_e32 v6, s0, v83
	v_lshlrev_b32_e32 v158, 14, v6
	v_cvt_pk_bf16_f32 v2, v11, v9
	v_cvt_pk_bf16_f32 v3, v13, v15
	v_cvt_pk_bf16_f32 v4, v17, v19
	v_cvt_pk_bf16_f32 v5, v21, v25
	ds_read2_b32 v[8:9], v80 offset0:32 offset1:40
	ds_read2_b32 v[10:11], v80 offset0:97 offset1:105
	ds_read2_b32 v[12:13], v80 offset0:162 offset1:170
	ds_read2_b32 v[14:15], v80 offset0:227 offset1:235
	ds_read2_b32 v[16:17], v26 offset0:36 offset1:44
	ds_read2_b32 v[18:19], v26 offset0:101 offset1:109
	ds_read2_b32 v[20:21], v26 offset0:166 offset1:174
	ds_read2_b32 v[24:25], v26 offset0:231 offset1:239
	v_lshl_add_u64 v[6:7], v[22:23], 0, v[158:159]
	global_store_dwordx4 v[6:7], v[2:5], off nt
	v_or_b32_e32 v6, s0, v84
	v_lshlrev_b32_e32 v158, 14, v6
	s_waitcnt lgkmcnt(6)
	v_cvt_pk_bf16_f32 v2, v8, v10
	s_waitcnt lgkmcnt(4)
	v_cvt_pk_bf16_f32 v3, v12, v14
	s_waitcnt lgkmcnt(2)
	v_cvt_pk_bf16_f32 v4, v16, v18
	s_waitcnt lgkmcnt(0)
	v_cvt_pk_bf16_f32 v5, v20, v24
	v_lshl_add_u64 v[6:7], v[22:23], 0, v[158:159]
	global_store_dwordx4 v[6:7], v[2:5], off nt
	v_or_b32_e32 v6, s0, v85
	v_lshlrev_b32_e32 v158, 14, v6
	v_cvt_pk_bf16_f32 v2, v9, v11
	v_cvt_pk_bf16_f32 v3, v13, v15
	v_cvt_pk_bf16_f32 v4, v17, v19
	v_cvt_pk_bf16_f32 v5, v21, v25
	ds_read2_b32 v[8:9], v80 offset0:48 offset1:56
	ds_read2_b32 v[10:11], v80 offset0:113 offset1:121
	ds_read2_b32 v[12:13], v80 offset0:178 offset1:186
	ds_read2_b32 v[14:15], v80 offset0:243 offset1:251
	ds_read2_b32 v[16:17], v26 offset0:52 offset1:60
	ds_read2_b32 v[18:19], v26 offset0:117 offset1:125
	ds_read2_b32 v[20:21], v26 offset0:182 offset1:190
	ds_read2_b32 v[24:25], v26 offset0:247 offset1:255
	v_lshl_add_u64 v[6:7], v[22:23], 0, v[158:159]
	global_store_dwordx4 v[6:7], v[2:5], off nt
	v_or_b32_e32 v6, s0, v86
	v_lshlrev_b32_e32 v158, 14, v6
	s_waitcnt lgkmcnt(6)
	v_cvt_pk_bf16_f32 v2, v8, v10
	s_waitcnt lgkmcnt(4)
	v_cvt_pk_bf16_f32 v3, v12, v14
	s_waitcnt lgkmcnt(2)
	v_cvt_pk_bf16_f32 v4, v16, v18
	s_waitcnt lgkmcnt(0)
	v_cvt_pk_bf16_f32 v5, v20, v24
	v_lshl_add_u64 v[6:7], v[22:23], 0, v[158:159]
	global_store_dwordx4 v[6:7], v[2:5], off nt
	v_or_b32_e32 v6, s0, v87
	v_lshlrev_b32_e32 v158, 14, v6
	v_cvt_pk_bf16_f32 v2, v9, v11
	v_cvt_pk_bf16_f32 v3, v13, v15
	v_cvt_pk_bf16_f32 v4, v17, v19
	v_cvt_pk_bf16_f32 v5, v21, v25
	v_lshl_add_u64 v[6:7], v[22:23], 0, v[158:159]
	global_store_dwordx4 v[6:7], v[2:5], off nt
	s_waitcnt lgkmcnt(0)
	s_mov_b64 s[0:1], 0
.LBB0_175:
	s_andn2_b64 vcc, exec, s[0:1]
	s_cbranch_vccnz .LBB0_182
	s_load_dwordx2 s[22:23], s[18:19], 0x30
	s_load_dwordx2 s[16:17], s[18:19], 0x18
	s_add_i32 s0, s28, 0xe700
	s_lshr_b32 s0, s0, 1
	s_and_b32 s24, s0, 0x7fc0
	s_waitcnt lgkmcnt(0)
	s_cmp_lg_u64 s[22:23], 0
	s_cselect_b64 s[0:1], -1, 0
	s_cmp_eq_u64 s[22:23], 0
	s_cbranch_scc1 .LBB0_178
	s_lshl_b64 s[30:31], s[14:15], 2
	s_add_u32 s22, s22, s30
	v_or_b32_e32 v2, s24, v67
	s_addc_u32 s23, s23, s31
	v_lshlrev_b32_e32 v2, 2, v2
	global_load_dword v106, v2, s[22:23] nt
	s_branch .LBB0_179

; __device__ __forceinline__ void transpose_item(const float* W, const float* g, int K, int N, bf16* WT, LAS float* scr, int item, int lane) {
;     ...
;     const float gl = g ? g[k0 + lane] : 1.f;
; #pragma unroll
;     for (int i = 0; i < 16; ++i) w[i] = *(const f32x4*)(W + (size_t)(k0 + 4 * i + kr) * N + n0 + 4 * n4);
;     if (g) {
; #pragma unroll
;         for (int i = 0; i < 16; ++i) w[i] = w[i] * __shfl(gl, 4 * i + kr); }
.LBB0_179:
	s_add_u32 s22, s16, s12
	s_addc_u32 s17, s17, s13
	s_and_b32 s16, s21, 0x1fc0
	s_lshl_b32 s23, s16, 2
	s_add_u32 s22, s22, s23
	v_or_b32_e32 v4, s24, v76
	s_addc_u32 s23, s17, 0
	v_lshlrev_b32_e32 v158, 2, v66
	v_lshl_add_u64 v[2:3], s[22:23], 0, v[158:159]
	v_lshlrev_b32_e32 v158, 15, v4
	v_lshl_add_u64 v[58:59], v[2:3], 0, v[158:159]
	s_mov_b32 s17, 0x20000
	v_add_co_u32_e32 v6, vcc, s17, v58
	s_mov_b32 s17, 0x40000
	s_nop 0
	v_addc_co_u32_e32 v7, vcc, 0, v59, vcc
	v_add_co_u32_e32 v10, vcc, s17, v58
	s_mov_b32 s17, 0x60000
	s_nop 0
	v_addc_co_u32_e32 v11, vcc, 0, v59, vcc
	v_add_co_u32_e32 v12, vcc, s17, v58
	s_mov_b32 s17, 0x80000
	s_nop 0
	v_addc_co_u32_e32 v13, vcc, 0, v59, vcc
	v_add_co_u32_e32 v18, vcc, s17, v58
	s_mov_b32 s17, 0xa0000
	s_nop 0
	v_addc_co_u32_e32 v19, vcc, 0, v59, vcc
	v_add_co_u32_e32 v20, vcc, s17, v58
	s_mov_b32 s17, 0xc0000
	s_nop 0
	v_addc_co_u32_e32 v21, vcc, 0, v59, vcc
	v_add_co_u32_e32 v26, vcc, s17, v58
	s_mov_b32 s17, 0xe0000
	s_nop 0
	v_addc_co_u32_e32 v27, vcc, 0, v59, vcc
	v_add_co_u32_e32 v28, vcc, s17, v58
	s_mov_b32 s17, 0x100000
	s_nop 0
	v_addc_co_u32_e32 v29, vcc, 0, v59, vcc
	v_add_co_u32_e32 v34, vcc, s17, v58
	s_mov_b32 s17, 0x120000
	s_nop 0
	v_addc_co_u32_e32 v35, vcc, 0, v59, vcc
	v_add_co_u32_e32 v36, vcc, s17, v58
	s_mov_b32 s17, 0x140000
	s_nop 0
	v_addc_co_u32_e32 v37, vcc, 0, v59, vcc
	v_add_co_u32_e32 v42, vcc, s17, v58
	s_mov_b32 s17, 0x160000
	s_nop 0
	v_addc_co_u32_e32 v43, vcc, 0, v59, vcc
	v_add_co_u32_e32 v44, vcc, s17, v58
	s_mov_b32 s17, 0x180000
	s_nop 0
	v_addc_co_u32_e32 v45, vcc, 0, v59, vcc
	v_add_co_u32_e32 v50, vcc, s17, v58
	global_load_dwordx4 v[2:5], v[58:59], off nt
	s_nop 0
	global_load_dwordx4 v[6:9], v[6:7], off nt
	v_addc_co_u32_e32 v51, vcc, 0, v59, vcc
	v_add_co_u32_e32 v52, vcc, 0x1a0000, v58
	global_load_dwordx4 v[14:17], v[10:11], off nt
	s_nop 0
	global_load_dwordx4 v[10:13], v[12:13], off nt
	v_addc_co_u32_e32 v53, vcc, 0, v59, vcc
	v_add_co_u32_e32 v60, vcc, 0x1c0000, v58
	global_load_dwordx4 v[22:25], v[18:19], off nt
	s_nop 0
	global_load_dwordx4 v[18:21], v[20:21], off nt
	v_addc_co_u32_e32 v61, vcc, 0, v59, vcc
	v_add_co_u32_e32 v58, vcc, 0x1e0000, v58
	global_load_dwordx4 v[30:33], v[26:27], off nt
	s_nop 0
	global_load_dwordx4 v[26:29], v[28:29], off nt
	v_addc_co_u32_e32 v59, vcc, 0, v59, vcc
	global_load_dwordx4 v[38:41], v[34:35], off nt
	s_nop 0
	global_load_dwordx4 v[34:37], v[36:37], off nt
	s_nop 0
	global_load_dwordx4 v[46:49], v[42:43], off nt
	s_nop 0
	global_load_dwordx4 v[42:45], v[44:45], off nt
	s_nop 0
	global_load_dwordx4 v[54:57], v[50:51], off nt
	s_nop 0
	global_load_dwordx4 v[50:53], v[52:53], off nt
	s_nop 0
	global_load_dwordx4 v[62:65], v[60:61], off nt
	s_nop 0
	global_load_dwordx4 v[58:61], v[58:59], off nt
	s_andn2_b64 vcc, exec, s[0:1]
	s_cbranch_vccnz .LBB0_181
	v_and_b32_e32 v107, 64, v195
	v_or_b32_e32 v108, v107, v76
	v_lshlrev_b32_e32 v108, 2, v108
	s_waitcnt vmcnt(0)
	ds_bpermute_b32 v108, v108, v106
	s_waitcnt lgkmcnt(0)
	v_pk_mul_f32 v[4:5], v[4:5], v[108:109] op_sel_hi:[1,0]
	v_pk_mul_f32 v[2:3], v[2:3], v[108:109] op_sel_hi:[1,0]
	v_or_b32_e32 v108, v107, v88
	v_lshlrev_b32_e32 v108, 2, v108
	ds_bpermute_b32 v108, v108, v106
	s_waitcnt lgkmcnt(0)
	v_pk_mul_f32 v[8:9], v[8:9], v[108:109] op_sel_hi:[1,0]
	v_pk_mul_f32 v[6:7], v[6:7], v[108:109] op_sel_hi:[1,0]
	v_or_b32_e32 v108, v107, v89
	v_lshlrev_b32_e32 v108, 2, v108
	ds_bpermute_b32 v108, v108, v106
	s_waitcnt lgkmcnt(0)
	v_pk_mul_f32 v[16:17], v[16:17], v[108:109] op_sel_hi:[1,0]
	v_pk_mul_f32 v[14:15], v[14:15], v[108:109] op_sel_hi:[1,0]
	v_or_b32_e32 v108, v107, v90
	v_lshlrev_b32_e32 v108, 2, v108
	ds_bpermute_b32 v108, v108, v106
	s_waitcnt lgkmcnt(0)
	v_pk_mul_f32 v[12:13], v[12:13], v[108:109] op_sel_hi:[1,0]
	v_pk_mul_f32 v[10:11], v[10:11], v[108:109] op_sel_hi:[1,0]
	v_or_b32_e32 v108, v107, v91
	v_lshlrev_b32_e32 v108, 2, v108
	ds_bpermute_b32 v108, v108, v106
	s_waitcnt lgkmcnt(0)
	v_pk_mul_f32 v[24:25], v[24:25], v[108:109] op_sel_hi:[1,0]
	v_pk_mul_f32 v[22:23], v[22:23], v[108:109] op_sel_hi:[1,0]
	v_or_b32_e32 v108, v107, v92
	v_lshlrev_b32_e32 v108, 2, v108
	ds_bpermute_b32 v108, v108, v106
	s_waitcnt lgkmcnt(0)
	v_pk_mul_f32 v[20:21], v[20:21], v[108:109] op_sel_hi:[1,0]
	v_pk_mul_f32 v[18:19], v[18:19], v[108:109] op_sel_hi:[1,0]
	v_or_b32_e32 v108, v107, v93
	v_lshlrev_b32_e32 v108, 2, v108
	ds_bpermute_b32 v108, v108, v106
	s_waitcnt lgkmcnt(0)
	v_pk_mul_f32 v[32:33], v[32:33], v[108:109] op_sel_hi:[1,0]
	v_pk_mul_f32 v[30:31], v[30:31], v[108:109] op_sel_hi:[1,0]
	v_or_b32_e32 v108, v107, v94
	v_lshlrev_b32_e32 v108, 2, v108
	ds_bpermute_b32 v108, v108, v106
	s_waitcnt lgkmcnt(0)
	v_pk_mul_f32 v[28:29], v[28:29], v[108:109] op_sel_hi:[1,0]
	v_pk_mul_f32 v[26:27], v[26:27], v[108:109] op_sel_hi:[1,0]
	v_or_b32_e32 v108, v107, v95
	v_lshlrev_b32_e32 v108, 2, v108
	ds_bpermute_b32 v108, v108, v106
	s_waitcnt lgkmcnt(0)
	v_pk_mul_f32 v[40:41], v[40:41], v[108:109] op_sel_hi:[1,0]
	v_pk_mul_f32 v[38:39], v[38:39], v[108:109] op_sel_hi:[1,0]
	v_or_b32_e32 v108, v107, v96
	v_lshlrev_b32_e32 v108, 2, v108
	ds_bpermute_b32 v108, v108, v106
	s_waitcnt lgkmcnt(0)
	v_pk_mul_f32 v[36:37], v[36:37], v[108:109] op_sel_hi:[1,0]
	v_pk_mul_f32 v[34:35], v[34:35], v[108:109] op_sel_hi:[1,0]
	v_or_b32_e32 v108, v107, v97
	v_lshlrev_b32_e32 v108, 2, v108
	ds_bpermute_b32 v108, v108, v106
	s_waitcnt lgkmcnt(0)
	v_pk_mul_f32 v[48:49], v[48:49], v[108:109] op_sel_hi:[1,0]
	v_pk_mul_f32 v[46:47], v[46:47], v[108:109] op_sel_hi:[1,0]
	v_or_b32_e32 v108, v107, v98
	v_lshlrev_b32_e32 v108, 2, v108
	ds_bpermute_b32 v108, v108, v106
	s_waitcnt lgkmcnt(0)
	v_pk_mul_f32 v[44:45], v[44:45], v[108:109] op_sel_hi:[1,0]
	v_pk_mul_f32 v[42:43], v[42:43], v[108:109] op_sel_hi:[1,0]
	v_or_b32_e32 v108, v107, v99
	v_lshlrev_b32_e32 v108, 2, v108
	ds_bpermute_b32 v108, v108, v106
	s_waitcnt lgkmcnt(0)
	v_pk_mul_f32 v[56:57], v[56:57], v[108:109] op_sel_hi:[1,0]
	v_pk_mul_f32 v[54:55], v[54:55], v[108:109] op_sel_hi:[1,0]
	v_or_b32_e32 v108, v107, v100
	v_lshlrev_b32_e32 v108, 2, v108
	ds_bpermute_b32 v108, v108, v106
	s_waitcnt lgkmcnt(0)
	v_pk_mul_f32 v[52:53], v[52:53], v[108:109] op_sel_hi:[1,0]
	v_pk_mul_f32 v[50:51], v[50:51], v[108:109] op_sel_hi:[1,0]
	v_or_b32_e32 v108, v107, v101
	v_or_b32_e32 v107, v107, v102
	v_lshlrev_b32_e32 v108, 2, v108
	v_lshlrev_b32_e32 v107, 2, v107
	ds_bpermute_b32 v108, v108, v106
	ds_bpermute_b32 v106, v107, v106
	s_waitcnt lgkmcnt(1)
	v_pk_mul_f32 v[64:65], v[64:65], v[108:109] op_sel_hi:[1,0]
	v_pk_mul_f32 v[62:63], v[62:63], v[108:109] op_sel_hi:[1,0]
	s_waitcnt lgkmcnt(0)
	v_pk_mul_f32 v[60:61], v[60:61], v[106:107] op_sel_hi:[1,0]
	v_pk_mul_f32 v[58:59], v[58:59], v[106:107] op_sel_hi:[1,0]
; #define LAS __attribute__((address_space(3)))
; #define LDS_WAIT() asm volatile("s_waitcnt lgkmcnt(0)" ::: "memory")
; __device__ __forceinline__ unsigned pk2(float lo, float hi) { return pg8::cvt_pk_bf16(lo, hi); }
; __device__ __forceinline__ void transpose_item(const float* W, const float* g, int K, int N, bf16* WT, LAS float* scr, int item, int lane) {
;     ...
;     for (int i = 0; i < 16; ++i) { LAS float* d = scr + (4 * i + kr) * 65 + 4 * n4; d[0] = w[i].x; d[1] = w[i].y; d[2] = w[i].z; d[3] = w[i].w; }
;     LDS_WAIT(); asm volatile("" ::: "memory");
;     const int c = lane & 7;
; #pragma unroll
;     for (int j = 0; j < 8; ++j) { const int n = (lane >> 3) + 8 * j; const LAS float* s = scr + (8 * c) * 65 + n;
;         v4u o; o.x = pk2(s[0 * 65], s[1 * 65]); o.y = pk2(s[2 * 65], s[3 * 65]); o.z = pk2(s[4 * 65], s[5 * 65]); o.w = pk2(s[6 * 65], s[7 * 65]);
;         *(v4u*)(WT + (size_t)(n0 + n) * K + k0 + 8 * c) = o; }
;     LDS_WAIT(); asm volatile("" ::: "memory");
.LBB0_181:
	s_waitcnt vmcnt(0)
	v_add_u32_e32 v106, v77, v78
	ds_write2_b32 v106, v2, v3 offset1:1
	ds_write2_b32 v106, v4, v5 offset0:2 offset1:3
	ds_write2_b32 v105, v6, v7 offset1:1
	ds_write2_b32 v105, v8, v9 offset0:2 offset1:3
	v_add_u32_e32 v2, 0x410, v105
	ds_write2_b32 v2, v14, v15 offset1:1
	v_add_u32_e32 v2, 0x418, v105
	ds_write2_b32 v2, v16, v17 offset1:1
	v_add_u32_e32 v2, 0x820, v105
	ds_write2_b32 v2, v10, v11 offset1:1
	v_add_u32_e32 v2, 0x828, v105
	ds_write2_b32 v2, v12, v13 offset1:1
	v_add_u32_e32 v2, 0xc30, v105
	ds_write2_b32 v2, v22, v23 offset1:1
	v_add_u32_e32 v2, 0xc38, v105
	ds_write2_b32 v2, v24, v25 offset1:1
	v_add_u32_e32 v2, 0x1040, v105
	ds_write2_b32 v2, v18, v19 offset1:1
	v_add_u32_e32 v2, 0x1048, v105
	ds_write2_b32 v2, v20, v21 offset1:1
	v_add_u32_e32 v2, 0x1450, v105
	ds_write2_b32 v2, v30, v31 offset1:1
	ds_write2_b32 v103, v32, v33 offset0:2 offset1:3
	v_add_u32_e32 v2, 0x410, v103
	ds_write2_b32 v2, v26, v27 offset1:1
	v_add_u32_e32 v2, 0x418, v103
	ds_write2_b32 v2, v28, v29 offset1:1
	v_add_u32_e32 v2, 0x820, v103
	ds_write2_b32 v2, v38, v39 offset1:1
	v_add_u32_e32 v2, 0x828, v103
	ds_write2_b32 v2, v40, v41 offset1:1
	v_add_u32_e32 v2, 0xc30, v103
	ds_write2_b32 v2, v34, v35 offset1:1
	v_add_u32_e32 v2, 0xc38, v103
	ds_write2_b32 v2, v36, v37 offset1:1
	v_add_u32_e32 v2, 0x1040, v103
	ds_write2_b32 v2, v46, v47 offset1:1
	v_add_u32_e32 v2, 0x1048, v103
	ds_write2_b32 v2, v48, v49 offset1:1
	v_add_u32_e32 v2, 0x1450, v103
	ds_write2_b32 v2, v42, v43 offset1:1
	ds_write2_b32 v104, v44, v45 offset0:2 offset1:3
	v_add_u32_e32 v2, 0x410, v104
	ds_write2_b32 v2, v54, v55 offset1:1
	v_add_u32_e32 v2, 0x418, v104
	ds_write2_b32 v2, v56, v57 offset1:1
	v_add_u32_e32 v2, 0x820, v104
	ds_write2_b32 v2, v50, v51 offset1:1
	v_add_u32_e32 v2, 0x828, v104
	ds_write2_b32 v2, v52, v53 offset1:1
	v_add_u32_e32 v2, 0xc30, v104
	ds_write2_b32 v2, v62, v63 offset1:1
	v_add_u32_e32 v2, 0xc38, v104
	ds_write2_b32 v2, v64, v65 offset1:1
	v_add_u32_e32 v2, 0x1040, v104
	ds_write2_b32 v2, v58, v59 offset1:1
	v_add_u32_e32 v2, 0x1048, v104
	ds_write2_b32 v2, v60, v61 offset1:1
	s_waitcnt lgkmcnt(0)
	v_add_u32_e32 v26, 0x400, v80
	ds_read2_b32 v[6:7], v80 offset0:65 offset1:73
	ds_read2_b32 v[8:9], v80 offset1:8
	ds_read2_b32 v[10:11], v80 offset0:130 offset1:138
	ds_read2_b32 v[12:13], v80 offset0:195 offset1:203
	ds_read2_b32 v[14:15], v26 offset0:4 offset1:12
	ds_read2_b32 v[16:17], v26 offset0:69 offset1:77
	ds_read2_b32 v[18:19], v26 offset0:134 offset1:142
	ds_read2_b32 v[20:21], v26 offset0:199 offset1:207
	s_lshl_b32 s34, s24, 1
	s_waitcnt lgkmcnt(6)
	v_cvt_pk_bf16_f32 v2, v8, v6
	v_or_b32_e32 v6, s16, v79
	v_lshl_add_u64 v[22:23], v[70:71], 0, s[34:35]
	v_lshlrev_b32_e32 v158, 12, v6
	s_waitcnt lgkmcnt(4)
	v_cvt_pk_bf16_f32 v3, v10, v12
	s_waitcnt lgkmcnt(2)
	v_cvt_pk_bf16_f32 v4, v14, v16
	s_waitcnt lgkmcnt(0)
	v_cvt_pk_bf16_f32 v5, v18, v20
	v_lshl_add_u64 v[24:25], v[22:23], 0, v[158:159]
	global_store_dwordx4 v[24:25], v[2:5], off nt
	v_or_b32_e32 v6, s16, v81
	v_lshlrev_b32_e32 v158, 12, v6
	v_cvt_pk_bf16_f32 v2, v9, v7
	v_cvt_pk_bf16_f32 v3, v11, v13
	v_cvt_pk_bf16_f32 v4, v15, v17
	v_cvt_pk_bf16_f32 v5, v19, v21
	ds_read2_b32 v[8:9], v80 offset0:81 offset1:89
	ds_read2_b32 v[10:11], v80 offset0:16 offset1:24
	ds_read2_b32 v[12:13], v80 offset0:146 offset1:154
	ds_read2_b32 v[14:15], v80 offset0:211 offset1:219
	ds_read2_b32 v[16:17], v26 offset0:20 offset1:28
	ds_read2_b32 v[18:19], v26 offset0:85 offset1:93
	ds_read2_b32 v[20:21], v26 offset0:150 offset1:158
	ds_read2_b32 v[24:25], v26 offset0:215 offset1:223
	v_lshl_add_u64 v[6:7], v[22:23], 0, v[158:159]
	global_store_dwordx4 v[6:7], v[2:5], off nt
	v_or_b32_e32 v6, s16, v82
	v_lshlrev_b32_e32 v158, 12, v6
	s_waitcnt lgkmcnt(6)
	v_cvt_pk_bf16_f32 v2, v10, v8
	s_waitcnt lgkmcnt(4)
	v_cvt_pk_bf16_f32 v3, v12, v14
	s_waitcnt lgkmcnt(2)
	v_cvt_pk_bf16_f32 v4, v16, v18
	s_waitcnt lgkmcnt(0)
	v_cvt_pk_bf16_f32 v5, v20, v24
	v_lshl_add_u64 v[6:7], v[22:23], 0, v[158:159]
	global_store_dwordx4 v[6:7], v[2:5], off nt
	v_or_b32_e32 v6, s16, v83
	v_lshlrev_b32_e32 v158, 12, v6
	v_cvt_pk_bf16_f32 v2, v11, v9
	v_cvt_pk_bf16_f32 v3, v13, v15
	v_cvt_pk_bf16_f32 v4, v17, v19
	v_cvt_pk_bf16_f32 v5, v21, v25
	ds_read2_b32 v[8:9], v80 offset0:32 offset1:40
	ds_read2_b32 v[10:11], v80 offset0:97 offset1:105
	ds_read2_b32 v[12:13], v80 offset0:162 offset1:170
	ds_read2_b32 v[14:15], v80 offset0:227 offset1:235
	ds_read2_b32 v[16:17], v26 offset0:36 offset1:44
	ds_read2_b32 v[18:19], v26 offset0:101 offset1:109
	ds_read2_b32 v[20:21], v26 offset0:166 offset1:174
	ds_read2_b32 v[24:25], v26 offset0:231 offset1:239
	v_lshl_add_u64 v[6:7], v[22:23], 0, v[158:159]
	global_store_dwordx4 v[6:7], v[2:5], off nt
	v_or_b32_e32 v6, s16, v84
	v_lshlrev_b32_e32 v158, 12, v6
	s_waitcnt lgkmcnt(6)
	v_cvt_pk_bf16_f32 v2, v8, v10
	s_waitcnt lgkmcnt(4)
	v_cvt_pk_bf16_f32 v3, v12, v14
	s_waitcnt lgkmcnt(2)
	v_cvt_pk_bf16_f32 v4, v16, v18
	s_waitcnt lgkmcnt(0)
	v_cvt_pk_bf16_f32 v5, v20, v24
	v_lshl_add_u64 v[6:7], v[22:23], 0, v[158:159]
	global_store_dwordx4 v[6:7], v[2:5], off nt
	v_or_b32_e32 v6, s16, v85
	v_lshlrev_b32_e32 v158, 12, v6
	v_cvt_pk_bf16_f32 v2, v9, v11
	v_cvt_pk_bf16_f32 v3, v13, v15
	v_cvt_pk_bf16_f32 v4, v17, v19
	v_cvt_pk_bf16_f32 v5, v21, v25
	ds_read2_b32 v[8:9], v80 offset0:48 offset1:56
	ds_read2_b32 v[10:11], v80 offset0:113 offset1:121
	ds_read2_b32 v[12:13], v80 offset0:178 offset1:186
	ds_read2_b32 v[14:15], v80 offset0:243 offset1:251
	ds_read2_b32 v[16:17], v26 offset0:52 offset1:60
	ds_read2_b32 v[18:19], v26 offset0:117 offset1:125
	ds_read2_b32 v[20:21], v26 offset0:182 offset1:190
	ds_read2_b32 v[24:25], v26 offset0:247 offset1:255
	v_lshl_add_u64 v[6:7], v[22:23], 0, v[158:159]
	global_store_dwordx4 v[6:7], v[2:5], off nt
	v_or_b32_e32 v6, s16, v86
	v_lshlrev_b32_e32 v158, 12, v6
	s_waitcnt lgkmcnt(6)
	v_cvt_pk_bf16_f32 v2, v8, v10
	s_waitcnt lgkmcnt(4)
	v_cvt_pk_bf16_f32 v3, v12, v14
	s_waitcnt lgkmcnt(2)
	v_cvt_pk_bf16_f32 v4, v16, v18
	s_waitcnt lgkmcnt(0)
	v_cvt_pk_bf16_f32 v5, v20, v24
	v_lshl_add_u64 v[6:7], v[22:23], 0, v[158:159]
	global_store_dwordx4 v[6:7], v[2:5], off nt
	v_or_b32_e32 v6, s16, v87
	v_lshlrev_b32_e32 v158, 12, v6
	v_cvt_pk_bf16_f32 v2, v9, v11
	v_cvt_pk_bf16_f32 v3, v13, v15
	v_cvt_pk_bf16_f32 v4, v17, v19
	v_cvt_pk_bf16_f32 v5, v21, v25
	v_lshl_add_u64 v[6:7], v[22:23], 0, v[158:159]
	global_store_dwordx4 v[6:7], v[2:5], off nt
	s_waitcnt lgkmcnt(0)

; #define LAS __attribute__((address_space(3)))
; __device__ __forceinline__ void transpose_item(const float* W, const float* g, int K, int N, bf16* WT, LAS float* scr, int item, int lane) {
;     const int nblk = N / 64, kb = item / nblk, nb = item % nblk, k0 = 64 * kb, n0 = 64 * nb;
;     const int n4 = lane & 15, kr = lane >> 4;
;     f32x4 w[16];
;     const float gl = g ? g[k0 + lane] : 1.f;
; #pragma unroll
;     for (int i = 0; i < 16; ++i) w[i] = *(const f32x4*)(W + (size_t)(k0 + 4 * i + kr) * N + n0 + 4 * n4);
;     if (g) {
; #pragma unroll
;         for (int i = 0; i < 16; ++i) w[i] = w[i] * __shfl(gl, 4 * i + kr); }
; #pragma unroll
;     for (int i = 0; i < 16; ++i) { LAS float* d = scr + (4 * i + kr) * 65 + 4 * n4; d[0] = w[i].x; d[1] = w[i].y; d[2] = w[i].z; d[3] = w[i].w; }
.LBB0_183:
	s_andn2_b64 vcc, exec, s[0:1]
	s_cbranch_vccnz .LBB0_185
	s_load_dwordx2 s[0:1], s[18:19], 0x10
	v_lshlrev_b32_e32 v158, 2, v66
	v_add_u32_e32 v106, v77, v78
	s_waitcnt lgkmcnt(0)
	s_add_u32 s16, s0, s4
	s_addc_u32 s1, s1, s5
	s_add_i32 s17, s29, 0x2800
	s_and_b32 s0, s21, 0x7c0
	s_and_b32 s22, s17, 0x1ffc0
	s_lshl_b32 s17, s0, 2
	s_add_u32 s16, s16, s17
	v_or_b32_e32 v4, s22, v76
	s_addc_u32 s17, s1, 0
	v_lshl_add_u64 v[2:3], s[16:17], 0, v[158:159]
	v_lshlrev_b32_e32 v158, 13, v4
	v_lshl_add_u64 v[62:63], v[2:3], 0, v[158:159]
	s_mov_b32 s1, 0x8000
	v_add_co_u32_e32 v6, vcc, s1, v62
	s_mov_b32 s1, 0x10000
	s_nop 0
	v_addc_co_u32_e32 v7, vcc, 0, v63, vcc
	v_add_co_u32_e32 v10, vcc, s1, v62
	global_load_dwordx4 v[2:5], v[62:63], off nt
	s_nop 0
	global_load_dwordx4 v[6:9], v[6:7], off nt
	v_addc_co_u32_e32 v11, vcc, 0, v63, vcc
	s_mov_b32 s1, 0x18000
	v_add_co_u32_e32 v14, vcc, s1, v62
	s_mov_b32 s1, 0x20000
	s_nop 0
	v_addc_co_u32_e32 v15, vcc, 0, v63, vcc
	global_load_dwordx4 v[10:13], v[10:11], off nt
	s_nop 0
	global_load_dwordx4 v[14:17], v[14:15], off nt
	v_add_co_u32_e32 v18, vcc, s1, v62
	s_mov_b32 s1, 0x28000
	s_nop 0
	v_addc_co_u32_e32 v19, vcc, 0, v63, vcc
	v_add_co_u32_e32 v22, vcc, s1, v62
	s_mov_b32 s1, 0x30000
	s_nop 0
	v_addc_co_u32_e32 v23, vcc, 0, v63, vcc
	global_load_dwordx4 v[18:21], v[18:19], off nt
	s_nop 0
	global_load_dwordx4 v[22:25], v[22:23], off nt
	v_add_co_u32_e32 v26, vcc, s1, v62
	s_mov_b32 s1, 0x38000
	s_nop 0
	v_addc_co_u32_e32 v27, vcc, 0, v63, vcc
	v_add_co_u32_e32 v30, vcc, s1, v62
	s_mov_b32 s1, 0x40000
	s_nop 0
	v_addc_co_u32_e32 v31, vcc, 0, v63, vcc
	global_load_dwordx4 v[26:29], v[26:27], off nt
	s_nop 0
	global_load_dwordx4 v[30:33], v[30:31], off nt
	v_add_co_u32_e32 v34, vcc, s1, v62
	s_mov_b32 s1, 0x48000
	s_nop 0
	v_addc_co_u32_e32 v35, vcc, 0, v63, vcc
	v_add_co_u32_e32 v38, vcc, s1, v62
	s_mov_b32 s1, 0x50000
	s_nop 0
	v_addc_co_u32_e32 v39, vcc, 0, v63, vcc
	global_load_dwordx4 v[34:37], v[34:35], off nt
	s_nop 0
	global_load_dwordx4 v[38:41], v[38:39], off nt
	v_add_co_u32_e32 v42, vcc, s1, v62
	s_mov_b32 s1, 0x58000
	s_nop 0
	v_addc_co_u32_e32 v43, vcc, 0, v63, vcc
	v_add_co_u32_e32 v46, vcc, s1, v62
	s_mov_b32 s1, 0x60000
	s_nop 0
	v_addc_co_u32_e32 v47, vcc, 0, v63, vcc
	global_load_dwordx4 v[42:45], v[42:43], off nt
	s_nop 0
	global_load_dwordx4 v[46:49], v[46:47], off nt
	v_add_co_u32_e32 v50, vcc, s1, v62
	s_mov_b32 s1, 0x68000
	s_nop 0
	v_addc_co_u32_e32 v51, vcc, 0, v63, vcc
	global_load_dwordx4 v[50:53], v[50:51], off nt
	v_add_co_u32_e32 v54, vcc, s1, v62
	s_mov_b32 s1, 0x70000
	s_nop 0
	v_addc_co_u32_e32 v55, vcc, 0, v63, vcc
	global_load_dwordx4 v[54:57], v[54:55], off nt
	v_add_co_u32_e32 v58, vcc, s1, v62
	s_mov_b32 s1, 0x78000
	s_nop 0
	v_addc_co_u32_e32 v59, vcc, 0, v63, vcc
	global_load_dwordx4 v[58:61], v[58:59], off nt
	v_add_co_u32_e32 v62, vcc, s1, v62
	s_lshl_b32 s34, s22, 1
	s_nop 0
	v_addc_co_u32_e32 v63, vcc, 0, v63, vcc
	global_load_dwordx4 v[62:65], v[62:63], off nt
	s_waitcnt vmcnt(0)
	ds_write2_b32 v106, v2, v3 offset1:1
	ds_write2_b32 v106, v4, v5 offset0:2 offset1:3
	v_add_u32_e32 v2, 0x410, v106
	ds_write2_b32 v2, v6, v7 offset1:1
	v_add_u32_e32 v2, 0x418, v106
	ds_write2_b32 v2, v8, v9 offset1:1
	v_add_u32_e32 v2, 0x820, v106
	ds_write2_b32 v2, v10, v11 offset1:1
	v_add_u32_e32 v2, 0x828, v106
	ds_write2_b32 v2, v12, v13 offset1:1
	v_add_u32_e32 v2, 0xc30, v106
	ds_write2_b32 v2, v14, v15 offset1:1
	v_add_u32_e32 v2, 0xc38, v106
	ds_write2_b32 v2, v16, v17 offset1:1
	v_add_u32_e32 v2, 0x1040, v106
	ds_write2_b32 v2, v18, v19 offset1:1
	v_add_u32_e32 v2, 0x1048, v106
	ds_write2_b32 v2, v20, v21 offset1:1
	v_add_u32_e32 v2, 0x1450, v106
	ds_write2_b32 v2, v22, v23 offset1:1
	v_add_u32_e32 v2, 0x1458, v106
	ds_write2_b32 v2, v24, v25 offset1:1
	v_add_u32_e32 v2, 0x1860, v106
	v_lshl_add_u64 v[22:23], v[72:73], 0, s[34:35]
	ds_write2_b32 v2, v26, v27 offset1:1
	v_add_u32_e32 v2, 0x1868, v106
	ds_write2_b32 v2, v28, v29 offset1:1
	v_add_u32_e32 v2, 0x1c70, v106
	ds_write2_b32 v2, v30, v31 offset1:1
	v_add_u32_e32 v2, 0x1c78, v106
	ds_write2_b32 v2, v32, v33 offset1:1
	v_add_u32_e32 v2, 0x2080, v106
	v_add_u32_e32 v26, 0x400, v80
	ds_write2_b32 v2, v34, v35 offset1:1
	v_add_u32_e32 v2, 0x2088, v106
	ds_write2_b32 v2, v36, v37 offset1:1
	v_add_u32_e32 v2, 0x2490, v106
	ds_write2_b32 v2, v38, v39 offset1:1
	v_add_u32_e32 v2, 0x2498, v106
	ds_write2_b32 v2, v40, v41 offset1:1
	v_add_u32_e32 v2, 0x28a0, v106
	ds_write2_b32 v2, v42, v43 offset1:1
	v_add_u32_e32 v2, 0x28a8, v106
	ds_write2_b32 v2, v44, v45 offset1:1
	v_add_u32_e32 v2, 0x2cb0, v106
	ds_write2_b32 v2, v46, v47 offset1:1
	v_add_u32_e32 v2, 0x2cb8, v106
	ds_write2_b32 v2, v48, v49 offset1:1
	v_add_u32_e32 v2, 0x30c0, v106
	ds_write2_b32 v2, v50, v51 offset1:1
	v_add_u32_e32 v2, 0x30c8, v106
	ds_write2_b32 v2, v52, v53 offset1:1
	v_add_u32_e32 v2, 0x34d0, v106
	ds_write2_b32 v2, v54, v55 offset1:1
	v_add_u32_e32 v2, 0x34d8, v106
	ds_write2_b32 v2, v56, v57 offset1:1
	v_add_u32_e32 v2, 0x38e0, v106
	ds_write2_b32 v2, v58, v59 offset1:1
	v_add_u32_e32 v2, 0x38e8, v106
	ds_write2_b32 v2, v60, v61 offset1:1
	v_add_u32_e32 v2, 0x3cf0, v106
	ds_write2_b32 v2, v62, v63 offset1:1
	v_add_u32_e32 v2, 0x3cf8, v106
	ds_write2_b32 v2, v64, v65 offset1:1
	s_waitcnt lgkmcnt(0)
; #define LAS __attribute__((address_space(3)))
; #define LDS_WAIT() asm volatile("s_waitcnt lgkmcnt(0)" ::: "memory")
; __device__ __forceinline__ unsigned pk2(float lo, float hi) { return pg8::cvt_pk_bf16(lo, hi); }
; __device__ __forceinline__ void transpose_item(const float* W, const float* g, int K, int N, bf16* WT, LAS float* scr, int item, int lane) {
;     ...
;     LDS_WAIT(); asm volatile("" ::: "memory");
;     const int c = lane & 7;
; #pragma unroll
;     for (int j = 0; j < 8; ++j) { const int n = (lane >> 3) + 8 * j; const LAS float* s = scr + (8 * c) * 65 + n;
;         v4u o; o.x = pk2(s[0 * 65], s[1 * 65]); o.y = pk2(s[2 * 65], s[3 * 65]); o.z = pk2(s[4 * 65], s[5 * 65]); o.w = pk2(s[6 * 65], s[7 * 65]);
;         *(v4u*)(WT + (size_t)(n0 + n) * K + k0 + 8 * c) = o; }
;     LDS_WAIT(); asm volatile("" ::: "memory");
	ds_read2_b32 v[6:7], v80 offset0:65 offset1:73
	ds_read2_b32 v[8:9], v80 offset1:8
	ds_read2_b32 v[10:11], v80 offset0:130 offset1:138
	ds_read2_b32 v[12:13], v80 offset0:195 offset1:203
	ds_read2_b32 v[14:15], v26 offset0:4 offset1:12
	ds_read2_b32 v[16:17], v26 offset0:69 offset1:77
	ds_read2_b32 v[18:19], v26 offset0:134 offset1:142
	ds_read2_b32 v[20:21], v26 offset0:199 offset1:207
	s_waitcnt lgkmcnt(6)
	v_cvt_pk_bf16_f32 v2, v8, v6
	v_or_b32_e32 v6, s0, v79
	v_lshlrev_b32_e32 v158, 12, v6
	s_waitcnt lgkmcnt(4)
	v_cvt_pk_bf16_f32 v3, v10, v12
	s_waitcnt lgkmcnt(2)
	v_cvt_pk_bf16_f32 v4, v14, v16
	s_waitcnt lgkmcnt(0)
	v_cvt_pk_bf16_f32 v5, v18, v20
	v_lshl_add_u64 v[24:25], v[22:23], 0, v[158:159]
	global_store_dwordx4 v[24:25], v[2:5], off nt
	v_or_b32_e32 v6, s0, v81
	v_lshlrev_b32_e32 v158, 12, v6
	v_cvt_pk_bf16_f32 v2, v9, v7
	v_cvt_pk_bf16_f32 v3, v11, v13
	v_cvt_pk_bf16_f32 v4, v15, v17
	v_cvt_pk_bf16_f32 v5, v19, v21
	ds_read2_b32 v[8:9], v80 offset0:81 offset1:89
	ds_read2_b32 v[10:11], v80 offset0:16 offset1:24
	ds_read2_b32 v[12:13], v80 offset0:146 offset1:154
	ds_read2_b32 v[14:15], v80 offset0:211 offset1:219
	ds_read2_b32 v[16:17], v26 offset0:20 offset1:28
	ds_read2_b32 v[18:19], v26 offset0:85 offset1:93
	ds_read2_b32 v[20:21], v26 offset0:150 offset1:158
	ds_read2_b32 v[24:25], v26 offset0:215 offset1:223
	v_lshl_add_u64 v[6:7], v[22:23], 0, v[158:159]
	global_store_dwordx4 v[6:7], v[2:5], off nt
	v_or_b32_e32 v6, s0, v82
	v_lshlrev_b32_e32 v158, 12, v6
	s_waitcnt lgkmcnt(6)
	v_cvt_pk_bf16_f32 v2, v10, v8
	s_waitcnt lgkmcnt(4)
	v_cvt_pk_bf16_f32 v3, v12, v14
	s_waitcnt lgkmcnt(2)
	v_cvt_pk_bf16_f32 v4, v16, v18
	s_waitcnt lgkmcnt(0)
	v_cvt_pk_bf16_f32 v5, v20, v24
	v_lshl_add_u64 v[6:7], v[22:23], 0, v[158:159]
	global_store_dwordx4 v[6:7], v[2:5], off nt
	v_or_b32_e32 v6, s0, v83
	v_lshlrev_b32_e32 v158, 12, v6
	v_cvt_pk_bf16_f32 v2, v11, v9
	v_cvt_pk_bf16_f32 v3, v13, v15
	v_cvt_pk_bf16_f32 v4, v17, v19
	v_cvt_pk_bf16_f32 v5, v21, v25
	ds_read2_b32 v[8:9], v80 offset0:32 offset1:40
	ds_read2_b32 v[10:11], v80 offset0:97 offset1:105
	ds_read2_b32 v[12:13], v80 offset0:162 offset1:170
	ds_read2_b32 v[14:15], v80 offset0:227 offset1:235
	ds_read2_b32 v[16:17], v26 offset0:36 offset1:44
	ds_read2_b32 v[18:19], v26 offset0:101 offset1:109
	ds_read2_b32 v[20:21], v26 offset0:166 offset1:174
	ds_read2_b32 v[24:25], v26 offset0:231 offset1:239
	v_lshl_add_u64 v[6:7], v[22:23], 0, v[158:159]
	global_store_dwordx4 v[6:7], v[2:5], off nt
	v_or_b32_e32 v6, s0, v84
	v_lshlrev_b32_e32 v158, 12, v6
	s_waitcnt lgkmcnt(6)
	v_cvt_pk_bf16_f32 v2, v8, v10
	s_waitcnt lgkmcnt(4)
	v_cvt_pk_bf16_f32 v3, v12, v14
	s_waitcnt lgkmcnt(2)
	v_cvt_pk_bf16_f32 v4, v16, v18
	s_waitcnt lgkmcnt(0)
	v_cvt_pk_bf16_f32 v5, v20, v24
	v_lshl_add_u64 v[6:7], v[22:23], 0, v[158:159]
	global_store_dwordx4 v[6:7], v[2:5], off nt
	v_or_b32_e32 v6, s0, v85
	v_lshlrev_b32_e32 v158, 12, v6
	v_cvt_pk_bf16_f32 v2, v9, v11
	v_cvt_pk_bf16_f32 v3, v13, v15
	v_cvt_pk_bf16_f32 v4, v17, v19
	v_cvt_pk_bf16_f32 v5, v21, v25
	ds_read2_b32 v[8:9], v80 offset0:48 offset1:56
	ds_read2_b32 v[10:11], v80 offset0:113 offset1:121
	ds_read2_b32 v[12:13], v80 offset0:178 offset1:186
	ds_read2_b32 v[14:15], v80 offset0:243 offset1:251
	ds_read2_b32 v[16:17], v26 offset0:52 offset1:60
	ds_read2_b32 v[18:19], v26 offset0:117 offset1:125
	ds_read2_b32 v[20:21], v26 offset0:182 offset1:190
	ds_read2_b32 v[24:25], v26 offset0:247 offset1:255
	v_lshl_add_u64 v[6:7], v[22:23], 0, v[158:159]
	global_store_dwordx4 v[6:7], v[2:5], off nt
	v_or_b32_e32 v6, s0, v86
	v_lshlrev_b32_e32 v158, 12, v6
	s_waitcnt lgkmcnt(6)
	v_cvt_pk_bf16_f32 v2, v8, v10
	s_waitcnt lgkmcnt(4)
	v_cvt_pk_bf16_f32 v3, v12, v14
	s_waitcnt lgkmcnt(2)
	v_cvt_pk_bf16_f32 v4, v16, v18
	s_waitcnt lgkmcnt(0)
	v_cvt_pk_bf16_f32 v5, v20, v24
	v_lshl_add_u64 v[6:7], v[22:23], 0, v[158:159]
	global_store_dwordx4 v[6:7], v[2:5], off nt
	v_or_b32_e32 v6, s0, v87
	v_lshlrev_b32_e32 v158, 12, v6
	v_cvt_pk_bf16_f32 v2, v9, v11
	v_cvt_pk_bf16_f32 v3, v13, v15
	v_cvt_pk_bf16_f32 v4, v17, v19
	v_cvt_pk_bf16_f32 v5, v21, v25
	v_lshl_add_u64 v[6:7], v[22:23], 0, v[158:159]
	global_store_dwordx4 v[6:7], v[2:5], off nt
	s_waitcnt lgkmcnt(0)

; __device__ __forceinline__ void transpose_item(const float* W, const float* g, int K, int N, bf16* WT, LAS float* scr, int item, int lane) {
;     const int nblk = N / 64, kb = item / nblk, nb = item % nblk, k0 = 64 * kb, n0 = 64 * nb;
;     const int n4 = lane & 15, kr = lane >> 4;
;     f32x4 w[16];
;     const float gl = g ? g[k0 + lane] : 1.f;
; __device__ __forceinline__ void convert_item(const Ctx& X, int l, int r, LAS float* scr) {
;     if (r < I_IN) { transpose_item(X.in(1) + (size_t)l * D * INW, X.in(5) + l * D, D, INW, (bf16*)(X.ws + WS_WIN) + (size_t)l * INW * D, scr, r, X.lane); return; } r -= I_IN;
.LBB0_186:
	s_andn2_b64 vcc, exec, s[0:1]
	s_cbranch_vccnz .LBB0_170
	s_load_dwordx2 s[16:17], s[18:19], 0x8
	s_load_dwordx2 s[24:25], s[18:19], 0x28
	s_mul_hi_i32 s0, s28, 0x30c30c31
	s_lshr_b32 s1, s0, 31
	s_ashr_i32 s0, s0, 5
	s_add_i32 s1, s0, s1
	s_lshl_b32 s0, s1, 6
	s_waitcnt lgkmcnt(0)
	s_cmp_lg_u64 s[24:25], 0
	s_cselect_b64 s[22:23], -1, 0
	s_cmp_eq_u64 s[24:25], 0
	s_cbranch_scc1 .LBB0_189
	s_lshl_b64 s[30:31], s[14:15], 2
	s_add_u32 s24, s24, s30
	v_or_b32_e32 v2, s0, v67
	s_addc_u32 s25, s25, s31
	v_ashrrev_i32_e32 v3, 31, v2
	v_lshl_add_u64 v[2:3], v[2:3], 2, s[24:25]
	global_load_dword v106, v[2:3], off nt
	s_branch .LBB0_190

; __device__ __forceinline__ void transpose_item(const float* W, const float* g, int K, int N, bf16* WT, LAS float* scr, int item, int lane) {
;     ...
;     for (int i = 0; i < 16; ++i) w[i] = *(const f32x4*)(W + (size_t)(k0 + 4 * i + kr) * N + n0 + 4 * n4);
;     if (g) {
; #pragma unroll
;         for (int i = 0; i < 16; ++i) w[i] = w[i] * __shfl(gl, 4 * i + kr); }
.LBB0_190:
	s_mul_i32 s24, s86, 0x5400000
	s_add_u32 s30, s16, s24
	s_mul_hi_u32 s16, s86, 0x5400000
	s_mulk_i32 s1, 0xd600
	s_addc_u32 s31, s17, s16
	s_add_i32 s16, s21, s1
	s_ashr_i32 s17, s16, 31
	s_lshl_b64 s[24:25], s[16:17], 2
	s_add_u32 s24, s30, s24
	v_or_b32_e32 v14, s0, v76
	s_addc_u32 s25, s31, s25
	v_lshlrev_b32_e32 v158, 2, v66
	v_lshl_add_u64 v[2:3], s[24:25], 0, v[158:159]
	v_or_b32_e32 v6, 4, v14
	v_mad_i64_i32 v[4:5], s[24:25], v14, s33, v[2:3]
	v_mad_i64_i32 v[6:7], s[24:25], v6, s33, v[2:3]
	global_load_dwordx4 v[58:61], v[4:5], off nt
	global_load_dwordx4 v[50:53], v[6:7], off nt
	v_or_b32_e32 v4, 8, v14
	v_or_b32_e32 v6, 12, v14
	v_mad_i64_i32 v[4:5], s[24:25], v4, s33, v[2:3]
	v_mad_i64_i32 v[6:7], s[24:25], v6, s33, v[2:3]
	global_load_dwordx4 v[62:65], v[4:5], off nt
	global_load_dwordx4 v[42:45], v[6:7], off nt
	v_or_b32_e32 v4, 16, v14
	v_or_b32_e32 v6, 20, v14
	v_mad_i64_i32 v[4:5], s[24:25], v4, s33, v[2:3]
	v_mad_i64_i32 v[6:7], s[24:25], v6, s33, v[2:3]
	global_load_dwordx4 v[54:57], v[4:5], off nt
	global_load_dwordx4 v[34:37], v[6:7], off nt
	v_or_b32_e32 v4, 24, v14
	v_or_b32_e32 v6, 28, v14
	v_mad_i64_i32 v[4:5], s[24:25], v4, s33, v[2:3]
	v_mad_i64_i32 v[6:7], s[24:25], v6, s33, v[2:3]
	global_load_dwordx4 v[46:49], v[4:5], off nt
	global_load_dwordx4 v[26:29], v[6:7], off nt
	v_or_b32_e32 v4, 32, v14
	v_or_b32_e32 v6, 36, v14
	v_mad_i64_i32 v[4:5], s[24:25], v4, s33, v[2:3]
	v_mad_i64_i32 v[6:7], s[24:25], v6, s33, v[2:3]
	global_load_dwordx4 v[38:41], v[4:5], off nt
	global_load_dwordx4 v[18:21], v[6:7], off nt
	v_or_b32_e32 v4, 40, v14
	v_or_b32_e32 v6, 44, v14
	v_mad_i64_i32 v[4:5], s[24:25], v4, s33, v[2:3]
	v_mad_i64_i32 v[6:7], s[24:25], v6, s33, v[2:3]
	global_load_dwordx4 v[30:33], v[4:5], off nt
	global_load_dwordx4 v[10:13], v[6:7], off nt
	v_or_b32_e32 v4, 48, v14
	v_or_b32_e32 v6, 52, v14
	v_mad_i64_i32 v[4:5], s[24:25], v4, s33, v[2:3]
	v_mad_i64_i32 v[6:7], s[24:25], v6, s33, v[2:3]
	global_load_dwordx4 v[22:25], v[4:5], off nt
	s_nop 0
	global_load_dwordx4 v[6:9], v[6:7], off nt
	v_or_b32_e32 v4, 56, v14
	v_or_b32_e32 v14, 60, v14
	v_mad_i64_i32 v[4:5], s[24:25], v4, s33, v[2:3]
	v_mad_i64_i32 v[2:3], s[24:25], v14, s33, v[2:3]
	global_load_dwordx4 v[14:17], v[4:5], off nt
	s_nop 0
	global_load_dwordx4 v[2:5], v[2:3], off nt
	s_andn2_b64 vcc, exec, s[22:23]
	s_cbranch_vccnz .LBB0_169
	v_and_b32_e32 v107, 64, v195
	v_or_b32_e32 v108, v107, v76
	v_lshlrev_b32_e32 v108, 2, v108
	s_waitcnt vmcnt(0)
	ds_bpermute_b32 v108, v108, v106
	s_waitcnt lgkmcnt(0)
	v_pk_mul_f32 v[60:61], v[60:61], v[108:109] op_sel_hi:[1,0]
	v_pk_mul_f32 v[58:59], v[58:59], v[108:109] op_sel_hi:[1,0]
	v_or_b32_e32 v108, v107, v88
	v_lshlrev_b32_e32 v108, 2, v108
	ds_bpermute_b32 v108, v108, v106
	s_waitcnt lgkmcnt(0)
	v_pk_mul_f32 v[52:53], v[52:53], v[108:109] op_sel_hi:[1,0]
	v_pk_mul_f32 v[50:51], v[50:51], v[108:109] op_sel_hi:[1,0]
	v_or_b32_e32 v108, v107, v89
	v_lshlrev_b32_e32 v108, 2, v108
	ds_bpermute_b32 v108, v108, v106
	s_waitcnt lgkmcnt(0)
	v_pk_mul_f32 v[64:65], v[64:65], v[108:109] op_sel_hi:[1,0]
	v_pk_mul_f32 v[62:63], v[62:63], v[108:109] op_sel_hi:[1,0]
	v_or_b32_e32 v108, v107, v90
	v_lshlrev_b32_e32 v108, 2, v108
	ds_bpermute_b32 v108, v108, v106
	s_waitcnt lgkmcnt(0)
	v_pk_mul_f32 v[44:45], v[44:45], v[108:109] op_sel_hi:[1,0]
	v_pk_mul_f32 v[42:43], v[42:43], v[108:109] op_sel_hi:[1,0]
	v_or_b32_e32 v108, v107, v91
	v_lshlrev_b32_e32 v108, 2, v108
	ds_bpermute_b32 v108, v108, v106
	s_waitcnt lgkmcnt(0)
	v_pk_mul_f32 v[56:57], v[56:57], v[108:109] op_sel_hi:[1,0]
	v_pk_mul_f32 v[54:55], v[54:55], v[108:109] op_sel_hi:[1,0]
	v_or_b32_e32 v108, v107, v92
	v_lshlrev_b32_e32 v108, 2, v108
	ds_bpermute_b32 v108, v108, v106
	s_waitcnt lgkmcnt(0)
	v_pk_mul_f32 v[36:37], v[36:37], v[108:109] op_sel_hi:[1,0]
	v_pk_mul_f32 v[34:35], v[34:35], v[108:109] op_sel_hi:[1,0]
	v_or_b32_e32 v108, v107, v93
	v_lshlrev_b32_e32 v108, 2, v108
	ds_bpermute_b32 v108, v108, v106
	s_waitcnt lgkmcnt(0)
	v_pk_mul_f32 v[48:49], v[48:49], v[108:109] op_sel_hi:[1,0]
	v_pk_mul_f32 v[46:47], v[46:47], v[108:109] op_sel_hi:[1,0]
	v_or_b32_e32 v108, v107, v94
	v_lshlrev_b32_e32 v108, 2, v108
	ds_bpermute_b32 v108, v108, v106
	s_waitcnt lgkmcnt(0)
	v_pk_mul_f32 v[28:29], v[28:29], v[108:109] op_sel_hi:[1,0]
	v_pk_mul_f32 v[26:27], v[26:27], v[108:109] op_sel_hi:[1,0]
	v_or_b32_e32 v108, v107, v95
	v_lshlrev_b32_e32 v108, 2, v108
	ds_bpermute_b32 v108, v108, v106
	s_waitcnt lgkmcnt(0)
	v_pk_mul_f32 v[40:41], v[40:41], v[108:109] op_sel_hi:[1,0]
	v_pk_mul_f32 v[38:39], v[38:39], v[108:109] op_sel_hi:[1,0]
	v_or_b32_e32 v108, v107, v96
	v_lshlrev_b32_e32 v108, 2, v108
	ds_bpermute_b32 v108, v108, v106
	s_waitcnt lgkmcnt(0)
	v_pk_mul_f32 v[20:21], v[20:21], v[108:109] op_sel_hi:[1,0]
	v_pk_mul_f32 v[18:19], v[18:19], v[108:109] op_sel_hi:[1,0]
	v_or_b32_e32 v108, v107, v97
	v_lshlrev_b32_e32 v108, 2, v108
	ds_bpermute_b32 v108, v108, v106
	s_waitcnt lgkmcnt(0)
	v_pk_mul_f32 v[32:33], v[32:33], v[108:109] op_sel_hi:[1,0]
	v_pk_mul_f32 v[30:31], v[30:31], v[108:109] op_sel_hi:[1,0]
	v_or_b32_e32 v108, v107, v98
	v_lshlrev_b32_e32 v108, 2, v108
	ds_bpermute_b32 v108, v108, v106
	s_waitcnt lgkmcnt(0)
	v_pk_mul_f32 v[12:13], v[12:13], v[108:109] op_sel_hi:[1,0]
	v_pk_mul_f32 v[10:11], v[10:11], v[108:109] op_sel_hi:[1,0]
	v_or_b32_e32 v108, v107, v99
	v_lshlrev_b32_e32 v108, 2, v108
	ds_bpermute_b32 v108, v108, v106
	s_waitcnt lgkmcnt(0)
	v_pk_mul_f32 v[24:25], v[24:25], v[108:109] op_sel_hi:[1,0]
	v_pk_mul_f32 v[22:23], v[22:23], v[108:109] op_sel_hi:[1,0]
	v_or_b32_e32 v108, v107, v100
	v_lshlrev_b32_e32 v108, 2, v108
	ds_bpermute_b32 v108, v108, v106
	s_waitcnt lgkmcnt(0)
	v_pk_mul_f32 v[8:9], v[8:9], v[108:109] op_sel_hi:[1,0]
	v_pk_mul_f32 v[6:7], v[6:7], v[108:109] op_sel_hi:[1,0]
	v_or_b32_e32 v108, v107, v101
	v_or_b32_e32 v107, v107, v102
	v_lshlrev_b32_e32 v108, 2, v108
	v_lshlrev_b32_e32 v107, 2, v107
	ds_bpermute_b32 v108, v108, v106
	ds_bpermute_b32 v106, v107, v106
	s_waitcnt lgkmcnt(1)
	v_pk_mul_f32 v[16:17], v[16:17], v[108:109] op_sel_hi:[1,0]
	v_pk_mul_f32 v[14:15], v[14:15], v[108:109] op_sel_hi:[1,0]
	s_waitcnt lgkmcnt(0)
	v_pk_mul_f32 v[4:5], v[4:5], v[106:107] op_sel_hi:[1,0]
	v_pk_mul_f32 v[2:3], v[2:3], v[106:107] op_sel_hi:[1,0]
	s_branch .LBB0_169
